# merge phase: gate tile prefetched before the segment k-loop; gate reads batched, sigmoid via v_rcp+Newton
# speedup vs baseline: 1.1233x; 1.0170x over previous
; template <int MI, int NJ> ...
;     ...
;   if (!pre) G8LOADP(Ag, Bg);
;   G8STORE(0);
;   {
;     const u16* ga_ = (1 < nk) ? Ag + 64 : Ag + nAoff;
;     const u16* gb_ = (1 < nk) ? Bg + 64 : Bg + nBoff;
;     G8LOADP(ga_, gb_);
;   }
;   __syncthreads();
;   const int sw0 = ((lane >> 4) ^ (lane & 7)) * 8;
;   const int dsw = (sw0 ^ 32) - sw0;
;   const u16* ra_ = sA + (wm * (16 * MI) + (lane & 15)) * 64 + sw0;
;   const u16* rb_ = sB + (wn * (16 * NJ) + (lane & 15)) * 64 + sw0;
;   for (int kt = 0; kt < nk; ++kt) {
;     const int buf = kt & 1;
;     {
;       G8STORE(buf ^ 1);
;       const u16* ga_ = (kt + 2 < nk) ? Ag + (kt + 2) * 64 : Ag + nAoff;
;       const u16* gb_ = (kt + 2 < nk) ? Bg + (kt + 2) * 64 : Bg + nBoff;
;       G8LOADP(ga_, gb_);
;     }
;     __builtin_amdgcn_sched_barrier(0);
;     __builtin_amdgcn_s_setprio(1);
;     const u16* a = ra_ + buf * AROWS * 64;
;     const u16* b = rb_ + buf * BROWS * 64;
; __device__ __forceinline__ void phase_merge(const Params& p, u16* smem, volatile LAS unsigned* vb_) {
;     ...
;       for (int k = 0; k < 8; ++k) {
;         const int c = tid2 + 512 * k;
;         const int row = c >> 5, ch = c & 31;
;         *(uint4*)(smem + row * 264 + ch * 8) = *(const uint4*)(MG + (size_t)(mt * 128 + row) * 3072 + n * 1024 + nt * 256 + ch * 8);
;       }
.LBB0_25:
	s_lshl_b32 s13, s39, 9
	s_waitcnt vmcnt(5)
	ds_write_b128 v183, v[2:5]
	s_waitcnt vmcnt(3)
	ds_write_b128 v183, v[10:13] offset:8192
	ds_write_b128 v183, v[6:9] offset:32768
	s_waitcnt vmcnt(2)
	ds_write_b128 v183, v[14:17] offset:40960
	s_waitcnt vmcnt(1)
	ds_write_b128 v183, v[18:21] offset:49152
	s_waitcnt vmcnt(0)
	ds_write_b128 v183, v[22:25] offset:57344
	v_add_co_u32_e32 v6, vcc, s77, v28
	s_add_i32 s40, s13, 0x200
	s_nop 0
	v_addc_co_u32_e32 v7, vcc, 0, v29, vcc
	s_cmp_eq_u32 s39, 2
	v_add_co_u32_e32 v14, vcc, s77, v26
	s_cselect_b32 s44, 0, s40
	s_nop 0
	v_addc_co_u32_e32 v15, vcc, 0, v27, vcc
	s_cselect_b32 s40, s23, 0
	s_cselect_b32 s46, s36, 0
	s_sub_i32 s44, s44, s13
	v_add_co_u32_e32 v18, vcc, 0x60000, v26
	s_ashr_i32 s41, s40, 31
	s_ashr_i32 s45, s44, 31
	v_addc_co_u32_e32 v19, vcc, 0, v27, vcc
	v_lshl_add_u64 v[2:3], s[40:41], 1, v[28:29]
	s_lshl_b64 s[40:41], s[44:45], 1
	v_mov_b32_e32 v0, 0xc00
	v_add_co_u32_e32 v22, vcc, 0x90000, v26
	v_lshl_add_u64 v[172:173], v[2:3], 0, s[40:41]
	v_mad_i64_i32 v[2:3], s[44:45], s46, v0, v[26:27]
	v_addc_co_u32_e32 v23, vcc, 0, v27, vcc
	v_lshl_add_u64 v[176:177], v[2:3], 0, s[40:41]
	global_load_dwordx4 v[2:5], v[28:29], off offset:128
	global_load_dwordx4 v[10:13], v[6:7], off offset:128
	s_nop 0
	global_load_dwordx4 v[6:9], v[26:27], off offset:128
	v_mov_b32_e32 v26, 0
	global_load_dwordx4 v[14:17], v[14:15], off offset:128
	s_mov_b32 s12, 0
	global_load_dwordx4 v[18:21], v[18:19], off offset:128
	v_mov_b64_e32 v[178:179], v[132:133]
	global_load_dwordx4 v[22:25], v[22:23], off offset:128
	v_mov_b64_e32 v[180:181], v[128:129]
	v_mov_b32_e32 v27, v26
	v_mov_b32_e32 v28, v26
	v_mov_b32_e32 v29, v26
	v_mov_b32_e32 v30, v26
	v_mov_b32_e32 v31, v26
	v_mov_b32_e32 v32, v26
	v_mov_b32_e32 v33, v26
	v_mov_b32_e32 v34, v26
	v_mov_b32_e32 v35, v26
	v_mov_b32_e32 v36, v26
	v_mov_b32_e32 v37, v26
	v_mov_b32_e32 v38, v26
	v_mov_b32_e32 v39, v26
	v_mov_b32_e32 v40, v26
	v_mov_b32_e32 v41, v26
	v_mov_b32_e32 v42, v26
	v_mov_b32_e32 v43, v26
	v_mov_b32_e32 v44, v26
	v_mov_b32_e32 v45, v26
	v_mov_b32_e32 v46, v26
	v_mov_b32_e32 v47, v26
	v_mov_b32_e32 v48, v26
	v_mov_b32_e32 v49, v26
	v_mov_b32_e32 v50, v26
	v_mov_b32_e32 v51, v26
	v_mov_b32_e32 v52, v26
	v_mov_b32_e32 v53, v26
	v_mov_b32_e32 v54, v26
	v_mov_b32_e32 v55, v26
	v_mov_b32_e32 v56, v26
	v_mov_b32_e32 v57, v26
	v_mov_b32_e32 v58, v26
	v_mov_b32_e32 v59, v26
	v_mov_b32_e32 v60, v26
	v_mov_b32_e32 v61, v26
	v_mov_b32_e32 v62, v26
	v_mov_b32_e32 v63, v26
	v_mov_b32_e32 v64, v26
	v_mov_b32_e32 v65, v26
	v_mov_b32_e32 v66, v26
	v_mov_b32_e32 v67, v26
	v_mov_b32_e32 v68, v26
	v_mov_b32_e32 v69, v26
	v_mov_b32_e32 v70, v26
	v_mov_b32_e32 v71, v26
	v_mov_b32_e32 v72, v26
	v_mov_b32_e32 v73, v26
	v_mov_b32_e32 v74, v26
	v_mov_b32_e32 v75, v26
	v_mov_b32_e32 v76, v26
	v_mov_b32_e32 v77, v26
	v_mov_b32_e32 v78, v26
	v_mov_b32_e32 v79, v26
	v_mov_b32_e32 v80, v26
	v_mov_b32_e32 v81, v26
	v_mov_b32_e32 v82, v26
	v_mov_b32_e32 v83, v26
	v_mov_b32_e32 v84, v26
	v_mov_b32_e32 v85, v26
	v_mov_b32_e32 v86, v26
	v_mov_b32_e32 v87, v26
	v_mov_b32_e32 v88, v26
	v_mov_b32_e32 v89, v26
	s_lshl_b32 s47, s39, 11
	s_add_u32 s48, s37, s47
	s_addc_u32 s49, s38, 0
	s_mul_i32 s47, s22, 0x1800
	s_add_u32 s48, s48, s47
	s_addc_u32 s49, s49, 0
	v_lshrrev_b32_e32 v250, 5, v175
	v_and_b32_e32 v251, 31, v175
	v_mul_u32_u24_e32 v250, 0x1800, v250
	v_lshl_add_u32 v250, v251, 4, v250
	global_load_dwordx4 v[212:215], v250, s[48:49]
	s_add_u32 s50, s48, 0x18000
	s_addc_u32 s51, s49, 0
	global_load_dwordx4 v[216:219], v250, s[50:51]
	s_add_u32 s52, s50, 0x18000
	s_addc_u32 s53, s51, 0
	global_load_dwordx4 v[220:223], v250, s[52:53]
	s_add_u32 s48, s52, 0x18000
	s_addc_u32 s49, s53, 0
	global_load_dwordx4 v[224:227], v250, s[48:49]
	s_add_u32 s50, s48, 0x18000
	s_addc_u32 s51, s49, 0
	global_load_dwordx4 v[234:237], v250, s[50:51]
	s_add_u32 s52, s50, 0x18000
	s_addc_u32 s53, s51, 0
	global_load_dwordx4 v[238:241], v250, s[52:53]
	s_add_u32 s48, s52, 0x18000
	s_addc_u32 s49, s53, 0
	global_load_dwordx4 v[242:245], v250, s[48:49]
	s_add_u32 s50, s48, 0x18000
	s_addc_u32 s51, s49, 0
	global_load_dwordx4 v[246:249], v250, s[50:51]
	s_waitcnt lgkmcnt(0)
	s_barrier
.LBB0_26:
	s_and_b32 s13, s12, 1
	s_xor_b32 s40, s13, 1
	s_cmp_lt_u32 s12, 6
	v_lshl_add_u32 v0, s40, 14, v183
	s_cselect_b64 vcc, -1, 0
	v_lshl_add_u32 v187, s40, 15, v183
	s_waitcnt vmcnt(5)
	ds_write_b128 v0, v[2:5]
	s_waitcnt vmcnt(3)
	ds_write_b128 v0, v[10:13] offset:8192
	s_waitcnt vmcnt(3)
	ds_write_b128 v187, v[6:9] offset:32768
	s_waitcnt vmcnt(2)
	ds_write_b128 v187, v[14:17] offset:40960
	s_waitcnt vmcnt(1)
	ds_write_b128 v187, v[18:21] offset:49152
	s_waitcnt vmcnt(0)
	ds_write_b128 v187, v[22:25] offset:57344
	v_cndmask_b32_e32 v6, v172, v178, vcc
	v_cndmask_b32_e32 v7, v173, v179, vcc
	v_cndmask_b32_e32 v11, v177, v181, vcc
	v_cndmask_b32_e32 v10, v176, v180, vcc
	v_add_co_u32_e32 v12, vcc, s77, v6
	s_mov_b32 s40, 0x90000
	s_nop 0
	v_addc_co_u32_e32 v13, vcc, 0, v7, vcc
	v_add_co_u32_e32 v14, vcc, s77, v10
	global_load_dwordx4 v[2:5], v[6:7], off
	s_nop 0
	v_addc_co_u32_e32 v15, vcc, 0, v11, vcc
	v_add_co_u32_e32 v18, vcc, s54, v10
	global_load_dwordx4 v[6:9], v[10:11], off
	s_nop 0
	v_addc_co_u32_e32 v19, vcc, 0, v11, vcc
	v_add_co_u32_e32 v22, vcc, s40, v10
	s_nop 1
	v_addc_co_u32_e32 v23, vcc, 0, v11, vcc
	global_load_dwordx4 v[10:13], v[12:13], off
	s_nop 0
	global_load_dwordx4 v[14:17], v[14:15], off
	s_nop 0
	global_load_dwordx4 v[18:21], v[18:19], off
	s_nop 0
	global_load_dwordx4 v[22:25], v[22:23], off
	s_setprio 1
	v_lshl_add_u32 v0, s13, 14, v184
	v_lshl_or_b32 v187, s13, 15, v185
	ds_read_b128 v[188:191], v0
	ds_read_b128 v[192:195], v187 offset:32768
	ds_read_b128 v[196:199], v187 offset:34816
	ds_read_b128 v[204:207], v187 offset:36864
	ds_read_b128 v[208:211], v187 offset:38912
	s_waitcnt lgkmcnt(3)
; __device__ __forceinline__ float bf2f(u16 h) { return __uint_as_float(((u32)h) << 16); }
; __device__ __forceinline__ float sigmoidf_(float x) { return 1.0f / (1.0f + __expf(-x)); }
; template <int MI, int NJ> ...
;     ...
;         for (int i = 0; i < 4; ++i) af[i] = *(const bf16x8*)(a_ + (ih * 4 + i) * 16 * 64);
; #pragma unroll
;         for (int i = 0; i < 4; ++i)
; #pragma unroll
;           for (int j = 0; j < NJ; ++j) acc[ih * 4 + i][j] = mfma16(af[i], bfr[j], acc[ih * 4 + i][j]);
;       }
;     }
;     __builtin_amdgcn_s_setprio(0);
;     __builtin_amdgcn_sched_barrier(0);
;     __syncthreads();
; __device__ __forceinline__ void phase_merge(const Params& p, u16* smem, volatile LAS unsigned* vb_) {
;     ...
;       for (int k = 0; k < 8; ++k) {
;         const int c = tid2 + 512 * k;
;         const int row = c >> 5, ch = c & 31;
;         *(uint4*)(smem + row * 264 + ch * 8) = *(const uint4*)(MG + (size_t)(mt * 128 + row) * 3072 + n * 1024 + nt * 256 + ch * 8);
;       }
;       __syncthreads();
; #pragma unroll
;       for (int i = 0; i < 4; ++i)
; #pragma unroll
;         for (int j = 0; j < 4; ++j)
; #pragma unroll
;           for (int r = 0; r < 4; ++r) {
;             const float g = sigmoidf_(bf2f(smem[(wm * 64 + i * 16 + (lane >> 4) * 4 + r) * 264 + wn * 64 + j * 16 + (lane & 15)]));
;             tot[i][j][r] += g * acc[i][j][r];
;             if (r == 3) __builtin_amdgcn_sched_barrier(0);
;           }
	v_mfma_f32_16x16x32_bf16 v[86:89], v[188:191], v[192:195], v[86:89]
	v_add_u32_e32 v187, v187, v186
	s_waitcnt lgkmcnt(2)
	v_mfma_f32_16x16x32_bf16 v[82:85], v[188:191], v[196:199], v[82:85]
	s_waitcnt lgkmcnt(1)
	v_mfma_f32_16x16x32_bf16 v[78:81], v[188:191], v[204:207], v[78:81]
	s_waitcnt lgkmcnt(0)
	v_mfma_f32_16x16x32_bf16 v[74:77], v[188:191], v[208:211], v[74:77]
	ds_read_b128 v[188:191], v0 offset:2048
	s_waitcnt lgkmcnt(0)
	v_mfma_f32_16x16x32_bf16 v[70:73], v[188:191], v[192:195], v[70:73]
	v_mfma_f32_16x16x32_bf16 v[66:69], v[188:191], v[196:199], v[66:69]
	v_mfma_f32_16x16x32_bf16 v[62:65], v[188:191], v[204:207], v[62:65]
	v_mfma_f32_16x16x32_bf16 v[58:61], v[188:191], v[208:211], v[58:61]
	ds_read_b128 v[188:191], v0 offset:4096
	s_waitcnt lgkmcnt(0)
	v_mfma_f32_16x16x32_bf16 v[54:57], v[188:191], v[192:195], v[54:57]
	v_mfma_f32_16x16x32_bf16 v[50:53], v[188:191], v[196:199], v[50:53]
	v_mfma_f32_16x16x32_bf16 v[46:49], v[188:191], v[204:207], v[46:49]
	v_mfma_f32_16x16x32_bf16 v[42:45], v[188:191], v[208:211], v[42:45]
	ds_read_b128 v[188:191], v0 offset:6144
	v_add_u32_e32 v0, v0, v186
	s_waitcnt lgkmcnt(0)
	v_mfma_f32_16x16x32_bf16 v[38:41], v[188:191], v[192:195], v[38:41]
	ds_read_b128 v[192:195], v0
	v_mfma_f32_16x16x32_bf16 v[34:37], v[188:191], v[196:199], v[34:37]
	ds_read_b128 v[196:199], v187 offset:34816
	v_mfma_f32_16x16x32_bf16 v[30:33], v[188:191], v[204:207], v[30:33]
	ds_read_b128 v[204:207], v187 offset:36864
	v_mfma_f32_16x16x32_bf16 v[26:29], v[188:191], v[208:211], v[26:29]
	ds_read_b128 v[188:191], v187 offset:32768
	ds_read_b128 v[208:211], v187 offset:38912
	s_waitcnt lgkmcnt(1)
	v_mfma_f32_16x16x32_bf16 v[86:89], v[192:195], v[188:191], v[86:89]
	v_mfma_f32_16x16x32_bf16 v[82:85], v[192:195], v[196:199], v[82:85]
	v_mfma_f32_16x16x32_bf16 v[78:81], v[192:195], v[204:207], v[78:81]
	s_waitcnt lgkmcnt(0)
	v_mfma_f32_16x16x32_bf16 v[74:77], v[192:195], v[208:211], v[74:77]
	ds_read_b128 v[192:195], v0 offset:2048
	s_waitcnt lgkmcnt(0)
	v_mfma_f32_16x16x32_bf16 v[70:73], v[192:195], v[188:191], v[70:73]
	v_mfma_f32_16x16x32_bf16 v[66:69], v[192:195], v[196:199], v[66:69]
	v_mfma_f32_16x16x32_bf16 v[62:65], v[192:195], v[204:207], v[62:65]
	v_mfma_f32_16x16x32_bf16 v[58:61], v[192:195], v[208:211], v[58:61]
	ds_read_b128 v[192:195], v0 offset:4096
	s_waitcnt lgkmcnt(0)
	v_mfma_f32_16x16x32_bf16 v[54:57], v[192:195], v[188:191], v[54:57]
	v_mfma_f32_16x16x32_bf16 v[50:53], v[192:195], v[196:199], v[50:53]
	v_mfma_f32_16x16x32_bf16 v[46:49], v[192:195], v[204:207], v[46:49]
	v_mfma_f32_16x16x32_bf16 v[42:45], v[192:195], v[208:211], v[42:45]
	ds_read_b128 v[192:195], v0 offset:6144
	s_waitcnt lgkmcnt(0)
	v_mfma_f32_16x16x32_bf16 v[38:41], v[192:195], v[188:191], v[38:41]
	v_mfma_f32_16x16x32_bf16 v[34:37], v[192:195], v[196:199], v[34:37]
	v_mfma_f32_16x16x32_bf16 v[30:33], v[192:195], v[204:207], v[30:33]
	v_mfma_f32_16x16x32_bf16 v[26:29], v[192:195], v[208:211], v[26:29]
	s_setprio 0
	s_add_i32 s12, s12, 1
	v_lshl_add_u64 v[180:181], v[180:181], 0, s[26:27]
	s_cmp_lg_u32 s12, 8
	v_lshl_add_u64 v[178:179], v[178:179], 0, s[26:27]
	s_barrier
	s_cbranch_scc1 .LBB0_26
	v_lshrrev_b32_e32 v250, 5, v175
	v_and_b32_e32 v251, 31, v175
	v_mul_u32_u24_e32 v250, 0x210, v250
	v_lshl_add_u32 v250, v251, 4, v250
	s_waitcnt vmcnt(6)
	ds_write_b128 v250, v[212:215]
	ds_write_b128 v250, v[216:219] offset:8448
	ds_write_b128 v250, v[220:223] offset:16896
	ds_write_b128 v250, v[224:227] offset:25344
	ds_write_b128 v250, v[234:237] offset:33792
	ds_write_b128 v250, v[238:241] offset:42240
	ds_write_b128 v250, v[242:245] offset:50688
	ds_write_b128 v250, v[246:249] offset:59136
	s_waitcnt lgkmcnt(0)
	s_barrier
	ds_read_u16 v212, v94
	ds_read_u16 v213, v94 offset:528
	ds_read_u16 v214, v94 offset:1056
	ds_read_u16 v215, v94 offset:1584
	ds_read_u16 v216, v94 offset:32
	ds_read_u16 v217, v94 offset:560
	ds_read_u16 v218, v94 offset:1088
	ds_read_u16 v219, v94 offset:1616
	s_waitcnt lgkmcnt(0)
	ds_read_u16 v204, v94 offset:64
	ds_read_u16 v205, v94 offset:592
	ds_read_u16 v206, v94 offset:1120
	ds_read_u16 v207, v94 offset:1648
	ds_read_u16 v208, v94 offset:96
	ds_read_u16 v209, v94 offset:624
	ds_read_u16 v210, v94 offset:1152
	ds_read_u16 v211, v94 offset:1680
	v_lshlrev_b32_e32 v212, 16, v212
	v_lshlrev_b32_e32 v213, 16, v213
	v_lshlrev_b32_e32 v214, 16, v214
	v_lshlrev_b32_e32 v215, 16, v215
	v_lshlrev_b32_e32 v216, 16, v216
	v_lshlrev_b32_e32 v217, 16, v217
	v_lshlrev_b32_e32 v218, 16, v218
	v_lshlrev_b32_e32 v219, 16, v219
	v_mul_f32_e32 v212, 0xbfb8aa3b, v212
	v_mul_f32_e32 v213, 0xbfb8aa3b, v213
	v_mul_f32_e32 v214, 0xbfb8aa3b, v214
	v_mul_f32_e32 v215, 0xbfb8aa3b, v215
	v_mul_f32_e32 v216, 0xbfb8aa3b, v216
	v_mul_f32_e32 v217, 0xbfb8aa3b, v217
	v_mul_f32_e32 v218, 0xbfb8aa3b, v218
	v_mul_f32_e32 v219, 0xbfb8aa3b, v219
	v_min_f32_e32 v212, 0x42fc0000, v212
	v_min_f32_e32 v213, 0x42fc0000, v213
	v_min_f32_e32 v214, 0x42fc0000, v214
	v_min_f32_e32 v215, 0x42fc0000, v215
	v_min_f32_e32 v216, 0x42fc0000, v216
	v_min_f32_e32 v217, 0x42fc0000, v217
	v_min_f32_e32 v218, 0x42fc0000, v218
	v_min_f32_e32 v219, 0x42fc0000, v219
	v_exp_f32_e32 v212, v212
	v_exp_f32_e32 v213, v213
	v_exp_f32_e32 v214, v214
	v_exp_f32_e32 v215, v215
	v_exp_f32_e32 v216, v216
	v_exp_f32_e32 v217, v217
	v_exp_f32_e32 v218, v218
	v_exp_f32_e32 v219, v219
	v_add_f32_e32 v212, 1.0, v212
	v_add_f32_e32 v213, 1.0, v213
	v_add_f32_e32 v214, 1.0, v214
	v_add_f32_e32 v215, 1.0, v215
	v_add_f32_e32 v216, 1.0, v216
	v_add_f32_e32 v217, 1.0, v217
	v_add_f32_e32 v218, 1.0, v218
	v_add_f32_e32 v219, 1.0, v219
	v_rcp_f32_e32 v220, v212
	v_rcp_f32_e32 v221, v213
	v_rcp_f32_e32 v222, v214
	v_rcp_f32_e32 v223, v215
	v_rcp_f32_e32 v224, v216
	v_rcp_f32_e32 v225, v217
	v_rcp_f32_e32 v226, v218
	v_rcp_f32_e32 v227, v219
	v_fma_f32 v212, -v212, v220, 1.0
	v_fma_f32 v213, -v213, v221, 1.0
	v_fma_f32 v214, -v214, v222, 1.0
	v_fma_f32 v215, -v215, v223, 1.0
	v_fma_f32 v216, -v216, v224, 1.0
	v_fma_f32 v217, -v217, v225, 1.0
	v_fma_f32 v218, -v218, v226, 1.0
	v_fma_f32 v219, -v219, v227, 1.0
	v_fmac_f32_e32 v220, v212, v220
	v_fmac_f32_e32 v221, v213, v221
	v_fmac_f32_e32 v222, v214, v222
	v_fmac_f32_e32 v223, v215, v223
	v_fmac_f32_e32 v224, v216, v224
	v_fmac_f32_e32 v225, v217, v225
	v_fmac_f32_e32 v226, v218, v226
	v_fmac_f32_e32 v227, v219, v227
	v_fmac_f32_e32 v170, v86, v220
	v_fmac_f32_e32 v171, v87, v221
	v_fmac_f32_e32 v168, v88, v222
	v_fmac_f32_e32 v169, v89, v223
	v_fmac_f32_e32 v166, v82, v224
	v_fmac_f32_e32 v167, v83, v225
	v_fmac_f32_e32 v164, v84, v226
	v_fmac_f32_e32 v165, v85, v227
	s_waitcnt lgkmcnt(0)
; __device__ __forceinline__ float bf2f(u16 h) { return __uint_as_float(((u32)h) << 16); }
; __device__ __forceinline__ float sigmoidf_(float x) { return 1.0f / (1.0f + __expf(-x)); }
; __device__ __forceinline__ void phase_merge(const Params& p, u16* smem, volatile LAS unsigned* vb_) {
;     ...
; #pragma unroll
;       for (int i = 0; i < 4; ++i)
; #pragma unroll
;         for (int j = 0; j < 4; ++j)
; #pragma unroll
;           for (int r = 0; r < 4; ++r) {
;             const float g = sigmoidf_(bf2f(smem[(wm * 64 + i * 16 + (lane >> 4) * 4 + r) * 264 + wn * 64 + j * 16 + (lane & 15)]));
;             tot[i][j][r] += g * acc[i][j][r];
;             if (r == 3) __builtin_amdgcn_sched_barrier(0);
;           }
	ds_read_u16 v212, v94 offset:8448
	ds_read_u16 v213, v94 offset:8976
	ds_read_u16 v214, v94 offset:9504
	ds_read_u16 v215, v94 offset:10032
	ds_read_u16 v216, v94 offset:8480
	ds_read_u16 v217, v94 offset:9008
	ds_read_u16 v218, v94 offset:9536
	ds_read_u16 v219, v94 offset:10064
	v_lshlrev_b32_e32 v204, 16, v204
	v_lshlrev_b32_e32 v205, 16, v205
	v_lshlrev_b32_e32 v206, 16, v206
	v_lshlrev_b32_e32 v207, 16, v207
	v_lshlrev_b32_e32 v208, 16, v208
	v_lshlrev_b32_e32 v209, 16, v209
	v_lshlrev_b32_e32 v210, 16, v210
	v_lshlrev_b32_e32 v211, 16, v211
	v_mul_f32_e32 v204, 0xbfb8aa3b, v204
	v_mul_f32_e32 v205, 0xbfb8aa3b, v205
	v_mul_f32_e32 v206, 0xbfb8aa3b, v206
	v_mul_f32_e32 v207, 0xbfb8aa3b, v207
	v_mul_f32_e32 v208, 0xbfb8aa3b, v208
	v_mul_f32_e32 v209, 0xbfb8aa3b, v209
	v_mul_f32_e32 v210, 0xbfb8aa3b, v210
	v_mul_f32_e32 v211, 0xbfb8aa3b, v211
	v_min_f32_e32 v204, 0x42fc0000, v204
	v_min_f32_e32 v205, 0x42fc0000, v205
	v_min_f32_e32 v206, 0x42fc0000, v206
	v_min_f32_e32 v207, 0x42fc0000, v207
	v_min_f32_e32 v208, 0x42fc0000, v208
	v_min_f32_e32 v209, 0x42fc0000, v209
	v_min_f32_e32 v210, 0x42fc0000, v210
	v_min_f32_e32 v211, 0x42fc0000, v211
	v_exp_f32_e32 v204, v204
	v_exp_f32_e32 v205, v205
	v_exp_f32_e32 v206, v206
	v_exp_f32_e32 v207, v207
	v_exp_f32_e32 v208, v208
	v_exp_f32_e32 v209, v209
	v_exp_f32_e32 v210, v210
	v_exp_f32_e32 v211, v211
	v_add_f32_e32 v204, 1.0, v204
	v_add_f32_e32 v205, 1.0, v205
	v_add_f32_e32 v206, 1.0, v206
	v_add_f32_e32 v207, 1.0, v207
	v_add_f32_e32 v208, 1.0, v208
	v_add_f32_e32 v209, 1.0, v209
	v_add_f32_e32 v210, 1.0, v210
	v_add_f32_e32 v211, 1.0, v211
	v_rcp_f32_e32 v220, v204
	v_rcp_f32_e32 v221, v205
	v_rcp_f32_e32 v222, v206
	v_rcp_f32_e32 v223, v207
	v_rcp_f32_e32 v224, v208
	v_rcp_f32_e32 v225, v209
	v_rcp_f32_e32 v226, v210
	v_rcp_f32_e32 v227, v211
	v_fma_f32 v204, -v204, v220, 1.0
	v_fma_f32 v205, -v205, v221, 1.0
	v_fma_f32 v206, -v206, v222, 1.0
	v_fma_f32 v207, -v207, v223, 1.0
	v_fma_f32 v208, -v208, v224, 1.0
	v_fma_f32 v209, -v209, v225, 1.0
	v_fma_f32 v210, -v210, v226, 1.0
	v_fma_f32 v211, -v211, v227, 1.0
	v_fmac_f32_e32 v220, v204, v220
	v_fmac_f32_e32 v221, v205, v221
	v_fmac_f32_e32 v222, v206, v222
	v_fmac_f32_e32 v223, v207, v223
	v_fmac_f32_e32 v224, v208, v224
	v_fmac_f32_e32 v225, v209, v225
	v_fmac_f32_e32 v226, v210, v226
	v_fmac_f32_e32 v227, v211, v227
	v_fmac_f32_e32 v162, v78, v220
	v_fmac_f32_e32 v163, v79, v221
	v_fmac_f32_e32 v160, v80, v222
	v_fmac_f32_e32 v161, v81, v223
	v_fmac_f32_e32 v158, v74, v224
	v_fmac_f32_e32 v159, v75, v225
	v_fmac_f32_e32 v156, v76, v226
	v_fmac_f32_e32 v157, v77, v227
	s_waitcnt lgkmcnt(0)
	ds_read_u16 v204, v94 offset:8512
	ds_read_u16 v205, v94 offset:9040
	ds_read_u16 v206, v94 offset:9568
	ds_read_u16 v207, v94 offset:10096
	ds_read_u16 v208, v94 offset:8544
	ds_read_u16 v209, v94 offset:9072
	ds_read_u16 v210, v94 offset:9600
	ds_read_u16 v211, v94 offset:10128
	v_lshlrev_b32_e32 v212, 16, v212
	v_lshlrev_b32_e32 v213, 16, v213
	v_lshlrev_b32_e32 v214, 16, v214
	v_lshlrev_b32_e32 v215, 16, v215
	v_lshlrev_b32_e32 v216, 16, v216
	v_lshlrev_b32_e32 v217, 16, v217
	v_lshlrev_b32_e32 v218, 16, v218
	v_lshlrev_b32_e32 v219, 16, v219
	v_mul_f32_e32 v212, 0xbfb8aa3b, v212
	v_mul_f32_e32 v213, 0xbfb8aa3b, v213
	v_mul_f32_e32 v214, 0xbfb8aa3b, v214
	v_mul_f32_e32 v215, 0xbfb8aa3b, v215
	v_mul_f32_e32 v216, 0xbfb8aa3b, v216
	v_mul_f32_e32 v217, 0xbfb8aa3b, v217
	v_mul_f32_e32 v218, 0xbfb8aa3b, v218
	v_mul_f32_e32 v219, 0xbfb8aa3b, v219
	v_min_f32_e32 v212, 0x42fc0000, v212
	v_min_f32_e32 v213, 0x42fc0000, v213
	v_min_f32_e32 v214, 0x42fc0000, v214
	v_min_f32_e32 v215, 0x42fc0000, v215
	v_min_f32_e32 v216, 0x42fc0000, v216
	v_min_f32_e32 v217, 0x42fc0000, v217
	v_min_f32_e32 v218, 0x42fc0000, v218
	v_min_f32_e32 v219, 0x42fc0000, v219
	v_exp_f32_e32 v212, v212
	v_exp_f32_e32 v213, v213
	v_exp_f32_e32 v214, v214
	v_exp_f32_e32 v215, v215
	v_exp_f32_e32 v216, v216
	v_exp_f32_e32 v217, v217
	v_exp_f32_e32 v218, v218
	v_exp_f32_e32 v219, v219
	v_add_f32_e32 v212, 1.0, v212
	v_add_f32_e32 v213, 1.0, v213
	v_add_f32_e32 v214, 1.0, v214
	v_add_f32_e32 v215, 1.0, v215
	v_add_f32_e32 v216, 1.0, v216
	v_add_f32_e32 v217, 1.0, v217
	v_add_f32_e32 v218, 1.0, v218
	v_add_f32_e32 v219, 1.0, v219
	v_rcp_f32_e32 v220, v212
	v_rcp_f32_e32 v221, v213
	v_rcp_f32_e32 v222, v214
	v_rcp_f32_e32 v223, v215
	v_rcp_f32_e32 v224, v216
	v_rcp_f32_e32 v225, v217
	v_rcp_f32_e32 v226, v218
	v_rcp_f32_e32 v227, v219
	v_fma_f32 v212, -v212, v220, 1.0
	v_fma_f32 v213, -v213, v221, 1.0
	v_fma_f32 v214, -v214, v222, 1.0
	v_fma_f32 v215, -v215, v223, 1.0
	v_fma_f32 v216, -v216, v224, 1.0
	v_fma_f32 v217, -v217, v225, 1.0
	v_fma_f32 v218, -v218, v226, 1.0
	v_fma_f32 v219, -v219, v227, 1.0
	v_fmac_f32_e32 v220, v212, v220
	v_fmac_f32_e32 v221, v213, v221
	v_fmac_f32_e32 v222, v214, v222
	v_fmac_f32_e32 v223, v215, v223
	v_fmac_f32_e32 v224, v216, v224
	v_fmac_f32_e32 v225, v217, v225
	v_fmac_f32_e32 v226, v218, v226
	v_fmac_f32_e32 v227, v219, v227
	v_fmac_f32_e32 v154, v70, v220
	v_fmac_f32_e32 v155, v71, v221
	v_fmac_f32_e32 v152, v72, v222
	v_fmac_f32_e32 v153, v73, v223
	v_fmac_f32_e32 v150, v66, v224
	v_fmac_f32_e32 v151, v67, v225
	v_fmac_f32_e32 v148, v68, v226
	v_fmac_f32_e32 v149, v69, v227
	s_waitcnt lgkmcnt(0)
; __device__ __forceinline__ float bf2f(u16 h) { return __uint_as_float(((u32)h) << 16); }
; __device__ __forceinline__ float sigmoidf_(float x) { return 1.0f / (1.0f + __expf(-x)); }
; __device__ __forceinline__ void phase_merge(const Params& p, u16* smem, volatile LAS unsigned* vb_) {
;     ...
; #pragma unroll
;       for (int i = 0; i < 4; ++i)
; #pragma unroll
;         for (int j = 0; j < 4; ++j)
; #pragma unroll
;           for (int r = 0; r < 4; ++r) {
;             const float g = sigmoidf_(bf2f(smem[(wm * 64 + i * 16 + (lane >> 4) * 4 + r) * 264 + wn * 64 + j * 16 + (lane & 15)]));
;             tot[i][j][r] += g * acc[i][j][r];
;             if (r == 3) __builtin_amdgcn_sched_barrier(0);
;           }
	ds_read_u16 v212, v94 offset:16896
	ds_read_u16 v213, v94 offset:17424
	ds_read_u16 v214, v94 offset:17952
	ds_read_u16 v215, v94 offset:18480
	ds_read_u16 v216, v94 offset:16928
	ds_read_u16 v217, v94 offset:17456
	ds_read_u16 v218, v94 offset:17984
	ds_read_u16 v219, v94 offset:18512
	v_lshlrev_b32_e32 v204, 16, v204
	v_lshlrev_b32_e32 v205, 16, v205
	v_lshlrev_b32_e32 v206, 16, v206
	v_lshlrev_b32_e32 v207, 16, v207
	v_lshlrev_b32_e32 v208, 16, v208
	v_lshlrev_b32_e32 v209, 16, v209
	v_lshlrev_b32_e32 v210, 16, v210
	v_lshlrev_b32_e32 v211, 16, v211
	v_mul_f32_e32 v204, 0xbfb8aa3b, v204
	v_mul_f32_e32 v205, 0xbfb8aa3b, v205
	v_mul_f32_e32 v206, 0xbfb8aa3b, v206
	v_mul_f32_e32 v207, 0xbfb8aa3b, v207
	v_mul_f32_e32 v208, 0xbfb8aa3b, v208
	v_mul_f32_e32 v209, 0xbfb8aa3b, v209
	v_mul_f32_e32 v210, 0xbfb8aa3b, v210
	v_mul_f32_e32 v211, 0xbfb8aa3b, v211
	v_min_f32_e32 v204, 0x42fc0000, v204
	v_min_f32_e32 v205, 0x42fc0000, v205
	v_min_f32_e32 v206, 0x42fc0000, v206
	v_min_f32_e32 v207, 0x42fc0000, v207
	v_min_f32_e32 v208, 0x42fc0000, v208
	v_min_f32_e32 v209, 0x42fc0000, v209
	v_min_f32_e32 v210, 0x42fc0000, v210
	v_min_f32_e32 v211, 0x42fc0000, v211
	v_exp_f32_e32 v204, v204
	v_exp_f32_e32 v205, v205
	v_exp_f32_e32 v206, v206
	v_exp_f32_e32 v207, v207
	v_exp_f32_e32 v208, v208
	v_exp_f32_e32 v209, v209
	v_exp_f32_e32 v210, v210
	v_exp_f32_e32 v211, v211
	v_add_f32_e32 v204, 1.0, v204
	v_add_f32_e32 v205, 1.0, v205
	v_add_f32_e32 v206, 1.0, v206
	v_add_f32_e32 v207, 1.0, v207
	v_add_f32_e32 v208, 1.0, v208
	v_add_f32_e32 v209, 1.0, v209
	v_add_f32_e32 v210, 1.0, v210
	v_add_f32_e32 v211, 1.0, v211
	v_rcp_f32_e32 v220, v204
	v_rcp_f32_e32 v221, v205
	v_rcp_f32_e32 v222, v206
	v_rcp_f32_e32 v223, v207
	v_rcp_f32_e32 v224, v208
	v_rcp_f32_e32 v225, v209
	v_rcp_f32_e32 v226, v210
	v_rcp_f32_e32 v227, v211
	v_fma_f32 v204, -v204, v220, 1.0
	v_fma_f32 v205, -v205, v221, 1.0
	v_fma_f32 v206, -v206, v222, 1.0
	v_fma_f32 v207, -v207, v223, 1.0
	v_fma_f32 v208, -v208, v224, 1.0
	v_fma_f32 v209, -v209, v225, 1.0
	v_fma_f32 v210, -v210, v226, 1.0
	v_fma_f32 v211, -v211, v227, 1.0
	v_fmac_f32_e32 v220, v204, v220
	v_fmac_f32_e32 v221, v205, v221
	v_fmac_f32_e32 v222, v206, v222
	v_fmac_f32_e32 v223, v207, v223
	v_fmac_f32_e32 v224, v208, v224
	v_fmac_f32_e32 v225, v209, v225
	v_fmac_f32_e32 v226, v210, v226
	v_fmac_f32_e32 v227, v211, v227
	v_fmac_f32_e32 v146, v62, v220
	v_fmac_f32_e32 v147, v63, v221
	v_fmac_f32_e32 v144, v64, v222
	v_fmac_f32_e32 v145, v65, v223
	v_fmac_f32_e32 v138, v58, v224
	v_fmac_f32_e32 v139, v59, v225
	v_fmac_f32_e32 v136, v60, v226
	v_fmac_f32_e32 v137, v61, v227
	s_waitcnt lgkmcnt(0)
	ds_read_u16 v204, v94 offset:16960
	ds_read_u16 v205, v94 offset:17488
	ds_read_u16 v206, v94 offset:18016
	ds_read_u16 v207, v94 offset:18544
	ds_read_u16 v208, v94 offset:16992
	ds_read_u16 v209, v94 offset:17520
	ds_read_u16 v210, v94 offset:18048
	ds_read_u16 v211, v94 offset:18576
	v_lshlrev_b32_e32 v212, 16, v212
	v_lshlrev_b32_e32 v213, 16, v213
	v_lshlrev_b32_e32 v214, 16, v214
	v_lshlrev_b32_e32 v215, 16, v215
	v_lshlrev_b32_e32 v216, 16, v216
	v_lshlrev_b32_e32 v217, 16, v217
	v_lshlrev_b32_e32 v218, 16, v218
	v_lshlrev_b32_e32 v219, 16, v219
	v_mul_f32_e32 v212, 0xbfb8aa3b, v212
	v_mul_f32_e32 v213, 0xbfb8aa3b, v213
	v_mul_f32_e32 v214, 0xbfb8aa3b, v214
	v_mul_f32_e32 v215, 0xbfb8aa3b, v215
	v_mul_f32_e32 v216, 0xbfb8aa3b, v216
	v_mul_f32_e32 v217, 0xbfb8aa3b, v217
	v_mul_f32_e32 v218, 0xbfb8aa3b, v218
	v_mul_f32_e32 v219, 0xbfb8aa3b, v219
	v_min_f32_e32 v212, 0x42fc0000, v212
	v_min_f32_e32 v213, 0x42fc0000, v213
	v_min_f32_e32 v214, 0x42fc0000, v214
	v_min_f32_e32 v215, 0x42fc0000, v215
	v_min_f32_e32 v216, 0x42fc0000, v216
	v_min_f32_e32 v217, 0x42fc0000, v217
	v_min_f32_e32 v218, 0x42fc0000, v218
	v_min_f32_e32 v219, 0x42fc0000, v219
	v_exp_f32_e32 v212, v212
	v_exp_f32_e32 v213, v213
	v_exp_f32_e32 v214, v214
	v_exp_f32_e32 v215, v215
	v_exp_f32_e32 v216, v216
	v_exp_f32_e32 v217, v217
	v_exp_f32_e32 v218, v218
	v_exp_f32_e32 v219, v219
	v_add_f32_e32 v212, 1.0, v212
	v_add_f32_e32 v213, 1.0, v213
	v_add_f32_e32 v214, 1.0, v214
	v_add_f32_e32 v215, 1.0, v215
	v_add_f32_e32 v216, 1.0, v216
	v_add_f32_e32 v217, 1.0, v217
	v_add_f32_e32 v218, 1.0, v218
	v_add_f32_e32 v219, 1.0, v219
	v_rcp_f32_e32 v220, v212
	v_rcp_f32_e32 v221, v213
	v_rcp_f32_e32 v222, v214
	v_rcp_f32_e32 v223, v215
	v_rcp_f32_e32 v224, v216
	v_rcp_f32_e32 v225, v217
	v_rcp_f32_e32 v226, v218
	v_rcp_f32_e32 v227, v219
	v_fma_f32 v212, -v212, v220, 1.0
	v_fma_f32 v213, -v213, v221, 1.0
	v_fma_f32 v214, -v214, v222, 1.0
	v_fma_f32 v215, -v215, v223, 1.0
	v_fma_f32 v216, -v216, v224, 1.0
	v_fma_f32 v217, -v217, v225, 1.0
	v_fma_f32 v218, -v218, v226, 1.0
	v_fma_f32 v219, -v219, v227, 1.0
	v_fmac_f32_e32 v220, v212, v220
	v_fmac_f32_e32 v221, v213, v221
	v_fmac_f32_e32 v222, v214, v222
	v_fmac_f32_e32 v223, v215, v223
	v_fmac_f32_e32 v224, v216, v224
	v_fmac_f32_e32 v225, v217, v225
	v_fmac_f32_e32 v226, v218, v226
	v_fmac_f32_e32 v227, v219, v227
	v_fmac_f32_e32 v134, v54, v220
	v_fmac_f32_e32 v135, v55, v221
	v_fmac_f32_e32 v130, v56, v222
	v_fmac_f32_e32 v131, v57, v223
	v_fmac_f32_e32 v126, v50, v224
	v_fmac_f32_e32 v127, v51, v225
	v_fmac_f32_e32 v124, v52, v226
	v_fmac_f32_e32 v125, v53, v227
	s_waitcnt lgkmcnt(0)
; __device__ __forceinline__ float bf2f(u16 h) { return __uint_as_float(((u32)h) << 16); }
; __device__ __forceinline__ float sigmoidf_(float x) { return 1.0f / (1.0f + __expf(-x)); }
; __device__ __forceinline__ void phase_merge(const Params& p, u16* smem, volatile LAS unsigned* vb_) {
;     ...
; #pragma unroll
;       for (int i = 0; i < 4; ++i)
; #pragma unroll
;         for (int j = 0; j < 4; ++j)
; #pragma unroll
;           for (int r = 0; r < 4; ++r) {
;             const float g = sigmoidf_(bf2f(smem[(wm * 64 + i * 16 + (lane >> 4) * 4 + r) * 264 + wn * 64 + j * 16 + (lane & 15)]));
;             tot[i][j][r] += g * acc[i][j][r];
;             if (r == 3) __builtin_amdgcn_sched_barrier(0);
;           }
	ds_read_u16 v212, v94 offset:25344
	ds_read_u16 v213, v94 offset:25872
	ds_read_u16 v214, v94 offset:26400
	ds_read_u16 v215, v94 offset:26928
	ds_read_u16 v216, v94 offset:25376
	ds_read_u16 v217, v94 offset:25904
	ds_read_u16 v218, v94 offset:26432
	ds_read_u16 v219, v94 offset:26960
	v_lshlrev_b32_e32 v204, 16, v204
	v_lshlrev_b32_e32 v205, 16, v205
	v_lshlrev_b32_e32 v206, 16, v206
	v_lshlrev_b32_e32 v207, 16, v207
	v_lshlrev_b32_e32 v208, 16, v208
	v_lshlrev_b32_e32 v209, 16, v209
	v_lshlrev_b32_e32 v210, 16, v210
	v_lshlrev_b32_e32 v211, 16, v211
	v_mul_f32_e32 v204, 0xbfb8aa3b, v204
	v_mul_f32_e32 v205, 0xbfb8aa3b, v205
	v_mul_f32_e32 v206, 0xbfb8aa3b, v206
	v_mul_f32_e32 v207, 0xbfb8aa3b, v207
	v_mul_f32_e32 v208, 0xbfb8aa3b, v208
	v_mul_f32_e32 v209, 0xbfb8aa3b, v209
	v_mul_f32_e32 v210, 0xbfb8aa3b, v210
	v_mul_f32_e32 v211, 0xbfb8aa3b, v211
	v_min_f32_e32 v204, 0x42fc0000, v204
	v_min_f32_e32 v205, 0x42fc0000, v205
	v_min_f32_e32 v206, 0x42fc0000, v206
	v_min_f32_e32 v207, 0x42fc0000, v207
	v_min_f32_e32 v208, 0x42fc0000, v208
	v_min_f32_e32 v209, 0x42fc0000, v209
	v_min_f32_e32 v210, 0x42fc0000, v210
	v_min_f32_e32 v211, 0x42fc0000, v211
	v_exp_f32_e32 v204, v204
	v_exp_f32_e32 v205, v205
	v_exp_f32_e32 v206, v206
	v_exp_f32_e32 v207, v207
	v_exp_f32_e32 v208, v208
	v_exp_f32_e32 v209, v209
	v_exp_f32_e32 v210, v210
	v_exp_f32_e32 v211, v211
	v_add_f32_e32 v204, 1.0, v204
	v_add_f32_e32 v205, 1.0, v205
	v_add_f32_e32 v206, 1.0, v206
	v_add_f32_e32 v207, 1.0, v207
	v_add_f32_e32 v208, 1.0, v208
	v_add_f32_e32 v209, 1.0, v209
	v_add_f32_e32 v210, 1.0, v210
	v_add_f32_e32 v211, 1.0, v211
	v_rcp_f32_e32 v220, v204
	v_rcp_f32_e32 v221, v205
	v_rcp_f32_e32 v222, v206
	v_rcp_f32_e32 v223, v207
	v_rcp_f32_e32 v224, v208
	v_rcp_f32_e32 v225, v209
	v_rcp_f32_e32 v226, v210
	v_rcp_f32_e32 v227, v211
	v_fma_f32 v204, -v204, v220, 1.0
	v_fma_f32 v205, -v205, v221, 1.0
	v_fma_f32 v206, -v206, v222, 1.0
	v_fma_f32 v207, -v207, v223, 1.0
	v_fma_f32 v208, -v208, v224, 1.0
	v_fma_f32 v209, -v209, v225, 1.0
	v_fma_f32 v210, -v210, v226, 1.0
	v_fma_f32 v211, -v211, v227, 1.0
	v_fmac_f32_e32 v220, v204, v220
	v_fmac_f32_e32 v221, v205, v221
	v_fmac_f32_e32 v222, v206, v222
	v_fmac_f32_e32 v223, v207, v223
	v_fmac_f32_e32 v224, v208, v224
	v_fmac_f32_e32 v225, v209, v225
	v_fmac_f32_e32 v226, v210, v226
	v_fmac_f32_e32 v227, v211, v227
	v_fmac_f32_e32 v122, v46, v220
	v_fmac_f32_e32 v123, v47, v221
	v_fmac_f32_e32 v120, v48, v222
	v_fmac_f32_e32 v121, v49, v223
	v_fmac_f32_e32 v118, v42, v224
	v_fmac_f32_e32 v119, v43, v225
	v_fmac_f32_e32 v116, v44, v226
	v_fmac_f32_e32 v117, v45, v227
	s_waitcnt lgkmcnt(0)
	ds_read_u16 v204, v94 offset:25408
	ds_read_u16 v205, v94 offset:25936
	ds_read_u16 v206, v94 offset:26464
	ds_read_u16 v207, v94 offset:26992
	ds_read_u16 v208, v94 offset:25440
	ds_read_u16 v209, v94 offset:25968
	ds_read_u16 v210, v94 offset:26496
	ds_read_u16 v211, v94 offset:27024
	v_lshlrev_b32_e32 v212, 16, v212
	v_lshlrev_b32_e32 v213, 16, v213
	v_lshlrev_b32_e32 v214, 16, v214
	v_lshlrev_b32_e32 v215, 16, v215
	v_lshlrev_b32_e32 v216, 16, v216
	v_lshlrev_b32_e32 v217, 16, v217
	v_lshlrev_b32_e32 v218, 16, v218
	v_lshlrev_b32_e32 v219, 16, v219
	v_mul_f32_e32 v212, 0xbfb8aa3b, v212
	v_mul_f32_e32 v213, 0xbfb8aa3b, v213
	v_mul_f32_e32 v214, 0xbfb8aa3b, v214
	v_mul_f32_e32 v215, 0xbfb8aa3b, v215
	v_mul_f32_e32 v216, 0xbfb8aa3b, v216
	v_mul_f32_e32 v217, 0xbfb8aa3b, v217
	v_mul_f32_e32 v218, 0xbfb8aa3b, v218
	v_mul_f32_e32 v219, 0xbfb8aa3b, v219
	v_min_f32_e32 v212, 0x42fc0000, v212
	v_min_f32_e32 v213, 0x42fc0000, v213
	v_min_f32_e32 v214, 0x42fc0000, v214
	v_min_f32_e32 v215, 0x42fc0000, v215
	v_min_f32_e32 v216, 0x42fc0000, v216
	v_min_f32_e32 v217, 0x42fc0000, v217
	v_min_f32_e32 v218, 0x42fc0000, v218
	v_min_f32_e32 v219, 0x42fc0000, v219
	v_exp_f32_e32 v212, v212
	v_exp_f32_e32 v213, v213
	v_exp_f32_e32 v214, v214
	v_exp_f32_e32 v215, v215
	v_exp_f32_e32 v216, v216
	v_exp_f32_e32 v217, v217
	v_exp_f32_e32 v218, v218
	v_exp_f32_e32 v219, v219
	v_add_f32_e32 v212, 1.0, v212
	v_add_f32_e32 v213, 1.0, v213
	v_add_f32_e32 v214, 1.0, v214
	v_add_f32_e32 v215, 1.0, v215
	v_add_f32_e32 v216, 1.0, v216
	v_add_f32_e32 v217, 1.0, v217
	v_add_f32_e32 v218, 1.0, v218
	v_add_f32_e32 v219, 1.0, v219
	v_rcp_f32_e32 v220, v212
	v_rcp_f32_e32 v221, v213
	v_rcp_f32_e32 v222, v214
	v_rcp_f32_e32 v223, v215
	v_rcp_f32_e32 v224, v216
	v_rcp_f32_e32 v225, v217
	v_rcp_f32_e32 v226, v218
	v_rcp_f32_e32 v227, v219
	v_fma_f32 v212, -v212, v220, 1.0
	v_fma_f32 v213, -v213, v221, 1.0
	v_fma_f32 v214, -v214, v222, 1.0
	v_fma_f32 v215, -v215, v223, 1.0
	v_fma_f32 v216, -v216, v224, 1.0
	v_fma_f32 v217, -v217, v225, 1.0
	v_fma_f32 v218, -v218, v226, 1.0
	v_fma_f32 v219, -v219, v227, 1.0
	v_fmac_f32_e32 v220, v212, v220
	v_fmac_f32_e32 v221, v213, v221
	v_fmac_f32_e32 v222, v214, v222
	v_fmac_f32_e32 v223, v215, v223
	v_fmac_f32_e32 v224, v216, v224
	v_fmac_f32_e32 v225, v217, v225
	v_fmac_f32_e32 v226, v218, v226
	v_fmac_f32_e32 v227, v219, v227
	v_fmac_f32_e32 v114, v38, v220
	v_fmac_f32_e32 v115, v39, v221
	v_fmac_f32_e32 v112, v40, v222
	v_fmac_f32_e32 v113, v41, v223
	v_fmac_f32_e32 v110, v34, v224
	v_fmac_f32_e32 v111, v35, v225
	v_fmac_f32_e32 v108, v36, v226
	v_fmac_f32_e32 v109, v37, v227
	s_waitcnt lgkmcnt(0)
; __device__ __forceinline__ float bf2f(u16 h) { return __uint_as_float(((u32)h) << 16); }
; __device__ __forceinline__ float sigmoidf_(float x) { return 1.0f / (1.0f + __expf(-x)); }
; __device__ __forceinline__ void phase_merge(const Params& p, u16* smem, volatile LAS unsigned* vb_) {
;     ...
; #pragma unroll
;       for (int i = 0; i < 4; ++i)
; #pragma unroll
;         for (int j = 0; j < 4; ++j)
; #pragma unroll
;           for (int r = 0; r < 4; ++r) {
;             const float g = sigmoidf_(bf2f(smem[(wm * 64 + i * 16 + (lane >> 4) * 4 + r) * 264 + wn * 64 + j * 16 + (lane & 15)]));
;             tot[i][j][r] += g * acc[i][j][r];
;             if (r == 3) __builtin_amdgcn_sched_barrier(0);
;           }
;       __syncthreads();
;     }
; #pragma unroll
;     for (int i = 0; i < 4; ++i)
; #pragma unroll
;       for (int j = 0; j < 4; ++j)
; #pragma unroll
;         for (int r = 0; r < 4; ++r)
;           smem[(wm * 64 + i * 16 + (lane >> 4) * 4 + r) * 264 + wn * 64 + j * 16 + (lane & 15)] = f2bf(tot[i][j][r]);
	v_lshlrev_b32_e32 v204, 16, v204
	v_lshlrev_b32_e32 v205, 16, v205
	v_lshlrev_b32_e32 v206, 16, v206
	v_lshlrev_b32_e32 v207, 16, v207
	v_lshlrev_b32_e32 v208, 16, v208
	v_lshlrev_b32_e32 v209, 16, v209
	v_lshlrev_b32_e32 v210, 16, v210
	v_lshlrev_b32_e32 v211, 16, v211
	v_mul_f32_e32 v204, 0xbfb8aa3b, v204
	v_mul_f32_e32 v205, 0xbfb8aa3b, v205
	v_mul_f32_e32 v206, 0xbfb8aa3b, v206
	v_mul_f32_e32 v207, 0xbfb8aa3b, v207
	v_mul_f32_e32 v208, 0xbfb8aa3b, v208
	v_mul_f32_e32 v209, 0xbfb8aa3b, v209
	v_mul_f32_e32 v210, 0xbfb8aa3b, v210
	v_mul_f32_e32 v211, 0xbfb8aa3b, v211
	v_min_f32_e32 v204, 0x42fc0000, v204
	v_min_f32_e32 v205, 0x42fc0000, v205
	v_min_f32_e32 v206, 0x42fc0000, v206
	v_min_f32_e32 v207, 0x42fc0000, v207
	v_min_f32_e32 v208, 0x42fc0000, v208
	v_min_f32_e32 v209, 0x42fc0000, v209
	v_min_f32_e32 v210, 0x42fc0000, v210
	v_min_f32_e32 v211, 0x42fc0000, v211
	v_exp_f32_e32 v204, v204
	v_exp_f32_e32 v205, v205
	v_exp_f32_e32 v206, v206
	v_exp_f32_e32 v207, v207
	v_exp_f32_e32 v208, v208
	v_exp_f32_e32 v209, v209
	v_exp_f32_e32 v210, v210
	v_exp_f32_e32 v211, v211
	v_add_f32_e32 v204, 1.0, v204
	v_add_f32_e32 v205, 1.0, v205
	v_add_f32_e32 v206, 1.0, v206
	v_add_f32_e32 v207, 1.0, v207
	v_add_f32_e32 v208, 1.0, v208
	v_add_f32_e32 v209, 1.0, v209
	v_add_f32_e32 v210, 1.0, v210
	v_add_f32_e32 v211, 1.0, v211
	v_rcp_f32_e32 v220, v204
	v_rcp_f32_e32 v221, v205
	v_rcp_f32_e32 v222, v206
	v_rcp_f32_e32 v223, v207
	v_rcp_f32_e32 v224, v208
	v_rcp_f32_e32 v225, v209
	v_rcp_f32_e32 v226, v210
	v_rcp_f32_e32 v227, v211
	v_fma_f32 v204, -v204, v220, 1.0
	v_fma_f32 v205, -v205, v221, 1.0
	v_fma_f32 v206, -v206, v222, 1.0
	v_fma_f32 v207, -v207, v223, 1.0
	v_fma_f32 v208, -v208, v224, 1.0
	v_fma_f32 v209, -v209, v225, 1.0
	v_fma_f32 v210, -v210, v226, 1.0
	v_fma_f32 v211, -v211, v227, 1.0
	v_fmac_f32_e32 v220, v204, v220
	v_fmac_f32_e32 v221, v205, v221
	v_fmac_f32_e32 v222, v206, v222
	v_fmac_f32_e32 v223, v207, v223
	v_fmac_f32_e32 v224, v208, v224
	v_fmac_f32_e32 v225, v209, v225
	v_fmac_f32_e32 v226, v210, v226
	v_fmac_f32_e32 v227, v211, v227
	v_fmac_f32_e32 v106, v30, v220
	v_fmac_f32_e32 v107, v31, v221
	v_fmac_f32_e32 v104, v32, v222
	v_fmac_f32_e32 v105, v33, v223
	v_fmac_f32_e32 v100, v26, v224
	v_fmac_f32_e32 v101, v27, v225
	v_fmac_f32_e32 v102, v28, v226
	v_fmac_f32_e32 v103, v29, v227
	s_add_i32 s39, s39, 1
	v_lshl_add_u64 v[128:129], v[128:129], 0, s[18:19]
	v_lshl_add_u64 v[132:133], v[132:133], 0, s[18:19]
	s_cmp_eq_u32 s39, 3
	s_mov_b64 s[12:13], -1
	s_barrier
	s_cbranch_scc0 .LBB0_23
	v_cvt_pk_bf16_f32 v0, v170, s0
	ds_write_b16 v94, v0
	v_cvt_pk_bf16_f32 v0, v171, s0
	ds_write_b16 v94, v0 offset:528
	v_cvt_pk_bf16_f32 v0, v168, s0
	ds_write_b16 v94, v0 offset:1056
	v_cvt_pk_bf16_f32 v0, v169, s0
	ds_write_b16 v94, v0 offset:1584
	v_cvt_pk_bf16_f32 v0, v166, s0
	ds_write_b16 v94, v0 offset:32
	v_cvt_pk_bf16_f32 v0, v167, s0
	ds_write_b16 v94, v0 offset:560
	v_cvt_pk_bf16_f32 v0, v164, s0
	ds_write_b16 v94, v0 offset:1088
	v_cvt_pk_bf16_f32 v0, v165, s0
	ds_write_b16 v94, v0 offset:1616
	v_cvt_pk_bf16_f32 v0, v162, s0
	ds_write_b16 v94, v0 offset:64
	v_cvt_pk_bf16_f32 v0, v163, s0
	ds_write_b16 v94, v0 offset:592
	v_cvt_pk_bf16_f32 v0, v160, s0
	ds_write_b16 v94, v0 offset:1120
	v_cvt_pk_bf16_f32 v0, v161, s0
	ds_write_b16 v94, v0 offset:1648
	v_cvt_pk_bf16_f32 v0, v158, s0
	ds_write_b16 v94, v0 offset:96
	v_cvt_pk_bf16_f32 v0, v159, s0
	ds_write_b16 v94, v0 offset:624
	v_cvt_pk_bf16_f32 v0, v156, s0
	ds_write_b16 v94, v0 offset:1152
	v_cvt_pk_bf16_f32 v0, v157, s0
	ds_write_b16 v94, v0 offset:1680
	v_cvt_pk_bf16_f32 v0, v154, s0
	ds_write_b16 v94, v0 offset:8448
	v_cvt_pk_bf16_f32 v0, v155, s0
	ds_write_b16 v94, v0 offset:8976
	v_cvt_pk_bf16_f32 v0, v152, s0
	ds_write_b16 v94, v0 offset:9504
	v_cvt_pk_bf16_f32 v0, v153, s0
	ds_write_b16 v94, v0 offset:10032
	v_cvt_pk_bf16_f32 v0, v150, s0
	ds_write_b16 v94, v0 offset:8480
	v_cvt_pk_bf16_f32 v0, v151, s0
	ds_write_b16 v94, v0 offset:9008
	v_cvt_pk_bf16_f32 v0, v148, s0
	ds_write_b16 v94, v0 offset:9536
	v_cvt_pk_bf16_f32 v0, v149, s0
	ds_write_b16 v94, v0 offset:10064
	v_cvt_pk_bf16_f32 v0, v146, s0
	ds_write_b16 v94, v0 offset:8512
	v_cvt_pk_bf16_f32 v0, v147, s0
	ds_write_b16 v94, v0 offset:9040
	v_cvt_pk_bf16_f32 v0, v144, s0
	ds_write_b16 v94, v0 offset:9568
	v_cvt_pk_bf16_f32 v0, v145, s0
	ds_write_b16 v94, v0 offset:10096
	v_cvt_pk_bf16_f32 v0, v138, s0
	ds_write_b16 v94, v0 offset:8544
	v_cvt_pk_bf16_f32 v0, v139, s0
	ds_write_b16 v94, v0 offset:9072
	v_cvt_pk_bf16_f32 v0, v136, s0
	ds_write_b16 v94, v0 offset:9600
	v_cvt_pk_bf16_f32 v0, v137, s0
	ds_write_b16 v94, v0 offset:10128
	v_cvt_pk_bf16_f32 v0, v134, s0
	ds_write_b16 v94, v0 offset:16896
	v_cvt_pk_bf16_f32 v0, v135, s0
	ds_write_b16 v94, v0 offset:17424
	v_cvt_pk_bf16_f32 v0, v130, s0
	ds_write_b16 v94, v0 offset:17952
	v_cvt_pk_bf16_f32 v0, v131, s0
	ds_write_b16 v94, v0 offset:18480
	v_cvt_pk_bf16_f32 v0, v126, s0
	ds_write_b16 v94, v0 offset:16928
	v_cvt_pk_bf16_f32 v0, v127, s0
	ds_write_b16 v94, v0 offset:17456
	v_cvt_pk_bf16_f32 v0, v124, s0
	ds_write_b16 v94, v0 offset:17984
	v_cvt_pk_bf16_f32 v0, v125, s0
	ds_write_b16 v94, v0 offset:18512
	v_cvt_pk_bf16_f32 v0, v122, s0
	ds_write_b16 v94, v0 offset:16960
	v_cvt_pk_bf16_f32 v0, v123, s0
	ds_write_b16 v94, v0 offset:17488
	v_cvt_pk_bf16_f32 v0, v120, s0
	ds_write_b16 v94, v0 offset:18016
	v_cvt_pk_bf16_f32 v0, v121, s0
	ds_write_b16 v94, v0 offset:18544
	v_cvt_pk_bf16_f32 v0, v118, s0
	ds_write_b16 v94, v0 offset:16992
	v_cvt_pk_bf16_f32 v0, v119, s0
	ds_write_b16 v94, v0 offset:17520
	v_cvt_pk_bf16_f32 v0, v116, s0
	ds_write_b16 v94, v0 offset:18048
	v_cvt_pk_bf16_f32 v0, v117, s0
	ds_write_b16 v94, v0 offset:18576
	v_cvt_pk_bf16_f32 v0, v114, s0
	ds_write_b16 v94, v0 offset:25344
	v_cvt_pk_bf16_f32 v0, v115, s0
	ds_write_b16 v94, v0 offset:25872
	v_cvt_pk_bf16_f32 v0, v112, s0
	ds_write_b16 v94, v0 offset:26400
	v_cvt_pk_bf16_f32 v0, v113, s0
	ds_write_b16 v94, v0 offset:26928
	v_cvt_pk_bf16_f32 v0, v110, s0
	ds_write_b16 v94, v0 offset:25376
	v_cvt_pk_bf16_f32 v0, v111, s0
	ds_write_b16 v94, v0 offset:25904
	v_cvt_pk_bf16_f32 v0, v108, s0
	ds_write_b16 v94, v0 offset:26432
	v_cvt_pk_bf16_f32 v0, v109, s0
	ds_write_b16 v94, v0 offset:26960
	v_cvt_pk_bf16_f32 v0, v106, s0
	ds_write_b16 v94, v0 offset:25408
	v_cvt_pk_bf16_f32 v0, v107, s0
	ds_write_b16 v94, v0 offset:25936
	v_cvt_pk_bf16_f32 v0, v104, s0
	ds_write_b16 v94, v0 offset:26464
	v_cvt_pk_bf16_f32 v0, v105, s0
	ds_write_b16 v94, v0 offset:26992
	v_cvt_pk_bf16_f32 v0, v100, s0
	ds_write_b16 v94, v0 offset:25440
	v_cvt_pk_bf16_f32 v0, v101, s0
	ds_write_b16 v94, v0 offset:25968
	v_cvt_pk_bf16_f32 v0, v102, s0
	ds_write_b16 v94, v0 offset:26496
	v_cvt_pk_bf16_f32 v0, v103, s0
	v_mov_b32_e32 v38, v175
	v_readlane_b32 s12, v252, 38
	ds_write_b16 v94, v0 offset:27024
	s_waitcnt lgkmcnt(0)
	s_barrier
; #define RTID opaque_tid()
; __device__ __forceinline__ void phase_merge(const Params& p, u16* smem, volatile LAS unsigned* vb_) {
;     ...
;     const int tid3 = RTID;
; #pragma unroll
;     for (int k = 0; k < 8; ++k) {
;       const int c = tid3 + 512 * k;
;       const int row = c >> 5, ch = c & 31;
;       *(uint4*)(outp + (size_t)(mt * 128 + row) * 1024 + nt * 256 + ch * 8) = *(const uint4*)(smem + row * 264 + ch * 8);
;     }
;     __syncthreads();
	v_readlane_b32 s13, v252, 39
	v_lshlrev_b32_e32 v0, 4, v38
	s_add_u32 s12, s12, s42
	v_and_b32_e32 v0, 0x1f0, v0
	s_addc_u32 s13, s13, s43
	v_ashrrev_i32_e32 v28, 5, v38
	v_lshl_add_u64 v[34:35], s[12:13], 0, v[0:1]
	v_mad_u64_u32 v[26:27], s[12:13], v28, s2, v[0:1]
	v_add_u32_e32 v28, s22, v28
	v_ashrrev_i32_e32 v29, 31, v28
	v_lshlrev_b64 v[28:29], 11, v[28:29]
	v_lshl_add_u64 v[36:37], v[34:35], 0, v[28:29]
	ds_read_b128 v[26:29], v26
	v_add_u32_e32 v30, 0x200, v38
	v_ashrrev_i32_e32 v39, 5, v30
	v_mad_u64_u32 v[30:31], s[12:13], v39, s2, v[0:1]
	ds_read_b128 v[30:33], v30
	s_waitcnt lgkmcnt(1)
	global_store_dwordx4 v[36:37], v[26:29], off
	s_add_i32 s10, s10, s70
	s_and_b64 vcc, exec, s[0:1]
	v_add_u32_e32 v26, s22, v39
	v_ashrrev_i32_e32 v27, 31, v26
	v_lshlrev_b64 v[26:27], 11, v[26:27]
	v_lshl_add_u64 v[26:27], v[34:35], 0, v[26:27]
	s_waitcnt lgkmcnt(0)
	global_store_dwordx4 v[26:27], v[30:33], off
	v_add_u32_e32 v26, 0x400, v38
	v_ashrrev_i32_e32 v28, 5, v26
	v_mad_u64_u32 v[26:27], s[12:13], v28, s2, v[0:1]
	v_add_u32_e32 v28, s22, v28
	v_ashrrev_i32_e32 v29, 31, v28
	v_lshlrev_b64 v[28:29], 11, v[28:29]
	v_lshl_add_u64 v[36:37], v[34:35], 0, v[28:29]
	ds_read_b128 v[26:29], v26
	v_add_u32_e32 v30, 0x600, v38
	v_ashrrev_i32_e32 v39, 5, v30
	v_mad_u64_u32 v[30:31], s[12:13], v39, s2, v[0:1]
	ds_read_b128 v[30:33], v30
	s_waitcnt lgkmcnt(1)
	global_store_dwordx4 v[36:37], v[26:29], off
	s_nop 1
	v_add_u32_e32 v26, s22, v39
	v_ashrrev_i32_e32 v27, 31, v26
	v_lshlrev_b64 v[26:27], 11, v[26:27]
	v_lshl_add_u64 v[26:27], v[34:35], 0, v[26:27]
	s_waitcnt lgkmcnt(0)
	global_store_dwordx4 v[26:27], v[30:33], off
	v_add_u32_e32 v26, 0x800, v38
	v_ashrrev_i32_e32 v28, 5, v26
	v_mad_u64_u32 v[26:27], s[12:13], v28, s2, v[0:1]
	v_add_u32_e32 v28, s22, v28
	v_ashrrev_i32_e32 v29, 31, v28
	v_lshlrev_b64 v[28:29], 11, v[28:29]
	v_lshl_add_u64 v[36:37], v[34:35], 0, v[28:29]
	ds_read_b128 v[26:29], v26
	v_add_u32_e32 v30, 0xa00, v38
	v_ashrrev_i32_e32 v39, 5, v30
	v_mad_u64_u32 v[30:31], s[12:13], v39, s2, v[0:1]
	ds_read_b128 v[30:33], v30
	s_waitcnt lgkmcnt(1)
	global_store_dwordx4 v[36:37], v[26:29], off
	s_nop 1
	v_add_u32_e32 v26, s22, v39
	v_ashrrev_i32_e32 v27, 31, v26
	v_lshlrev_b64 v[26:27], 11, v[26:27]
	v_lshl_add_u64 v[26:27], v[34:35], 0, v[26:27]
	s_waitcnt lgkmcnt(0)
	global_store_dwordx4 v[26:27], v[30:33], off
	v_add_u32_e32 v26, 0xc00, v38
	v_ashrrev_i32_e32 v28, 5, v26
	v_mad_u64_u32 v[26:27], s[12:13], v28, s2, v[0:1]
	v_add_u32_e32 v28, s22, v28
	v_ashrrev_i32_e32 v29, 31, v28
	v_lshlrev_b64 v[28:29], 11, v[28:29]
	v_lshl_add_u64 v[36:37], v[34:35], 0, v[28:29]
	ds_read_b128 v[26:29], v26
	v_add_u32_e32 v30, 0xe00, v38
	v_ashrrev_i32_e32 v38, 5, v30
	v_mad_u64_u32 v[30:31], s[12:13], v38, s2, v[0:1]
	ds_read_b128 v[30:33], v30
	s_waitcnt lgkmcnt(1)
	global_store_dwordx4 v[36:37], v[26:29], off
	v_readlane_b32 s12, v254, 30
	s_add_i32 s21, s21, s12
	v_add_u32_e32 v26, s22, v38
	v_ashrrev_i32_e32 v27, 31, v26
	v_lshlrev_b64 v[26:27], 11, v[26:27]
	v_lshl_add_u64 v[26:27], v[34:35], 0, v[26:27]
	s_mov_b64 s[12:13], -1
	s_waitcnt lgkmcnt(0)
	global_store_dwordx4 v[26:27], v[30:33], off
	s_barrier
	s_cbranch_vccz .LBB0_22
